# attention head loop: sink logit load issued one block earlier into its own register (no exposed load round trip per head)
# speedup vs baseline: 1.0312x; 1.0011x over previous
; __device__ __forceinline__ void attn_item(Frame& F, int item) {
;     ...
;         for (int r = 0; r < 4; ++r) { if (!(l15 < 4 * quad + r)) sc[0][r] = NEG; if (!(l15 >= 4 * quad + r)) sc[8][r] = NEG; }
;         if (qb == 0) {
; #pragma unroll
;             for (int kt = 0; kt < 9; ++kt)
; #pragma unroll
;                 for (int r = 0; r < 4; ++r) if (16 * w + 16 * kt + 4 * quad + r < 128) sc[kt][r] = NEG;
;         }
;         const float sink = F.sinks[qh];
;         float m = sink;
; #pragma unroll
;         for (int kt = 0; kt < 9; ++kt)
; #pragma unroll
;             for (int r = 0; r < 4; ++r) m = fmaxf(m, sc[kt][r]);
;         m = fmaxf(m, __shfl_xor(m, 16)); m = fmaxf(m, __shfl_xor(m, 32));
;         float l = 0.f;
; #pragma unroll
;         for (int kt = 0; kt < 9; ++kt)
; #pragma unroll
;             for (int r = 0; r < 4; ++r) { const float p = __expf(sc[kt][r] - m); sc[kt][r] = p; l += p; }
;         l += __shfl_xor(l, 16); l += __shfl_xor(l, 32);
;         l += __expf(sink - m);
;         const float il = __builtin_amdgcn_rcpf(l);
.LBB0_489:
	s_and_b64 vcc, s[10:11], s[8:9]
	s_nop 4
	v_cndmask_b32_e32 v190, v190, v224, vcc
	s_and_b64 vcc, vcc, s[6:7]
	v_cndmask_b32_e32 v189, v189, v224, vcc
	s_and_b64 vcc, vcc, s[4:5]
	v_cndmask_b32_e32 v188, v188, v224, vcc
	v_cndmask_b32_e64 v191, v191, v224, s[10:11]
	s_waitcnt vmcnt(0)
	v_max3_f32 v201, v239, v186, v1
	v_max3_f32 v201, v201, v2, v3
	v_max3_f32 v201, v201, v182, v183
	v_max3_f32 v201, v201, v184, v185
	v_max3_f32 v201, v201, v178, v179
	v_max3_f32 v201, v201, v180, v181
	v_max3_f32 v201, v201, v174, v175
	v_max3_f32 v201, v201, v176, v177
	v_max3_f32 v201, v201, v170, v171
	v_max3_f32 v201, v201, v172, v173
	v_max3_f32 v201, v201, v166, v167
	v_max3_f32 v201, v201, v168, v169
	v_max3_f32 v201, v201, v162, v163
	v_max3_f32 v201, v201, v164, v165
	v_max3_f32 v201, v201, v158, v159
	v_max3_f32 v201, v201, v160, v161
	v_max3_f32 v201, v201, v188, v189
	v_max3_f32 v201, v201, v190, v191
	ds_bpermute_b32 v226, v207, v201
	s_waitcnt lgkmcnt(0)
	v_max_f32_e32 v226, v226, v226
	v_max_f32_e32 v201, v201, v226
	ds_bpermute_b32 v226, v208, v201
	s_waitcnt lgkmcnt(0)
	v_max_f32_e32 v226, v226, v226
	v_max_f32_e32 v201, v201, v226
	v_sub_f32_e32 v186, v186, v201
	v_sub_f32_e32 v1, v1, v201
	v_mul_f32_e32 v186, 0x3fb8aa3b, v186
	v_sub_f32_e32 v2, v2, v201
	v_mul_f32_e32 v1, 0x3fb8aa3b, v1
	v_exp_f32_e32 v186, v186
	v_sub_f32_e32 v3, v3, v201
	v_mul_f32_e32 v2, 0x3fb8aa3b, v2
	v_exp_f32_e32 v1, v1
	v_sub_f32_e32 v182, v182, v201
	v_sub_f32_e32 v162, v162, v201
	v_mul_f32_e32 v3, 0x3fb8aa3b, v3
	v_exp_f32_e32 v2, v2
	v_sub_f32_e32 v183, v183, v201
	v_mul_f32_e32 v182, 0x3fb8aa3b, v182
	v_mul_f32_e32 v162, 0x3fb8aa3b, v162
	v_exp_f32_e32 v3, v3
	v_sub_f32_e32 v184, v184, v201
	v_mul_f32_e32 v183, 0x3fb8aa3b, v183
	v_exp_f32_e32 v182, v182
	v_exp_f32_e32 v230, v162
	v_add_f32_e32 v162, 0, v186
	v_sub_f32_e32 v185, v185, v201
	v_mul_f32_e32 v184, 0x3fb8aa3b, v184
	v_exp_f32_e32 v183, v183
	v_add_f32_e32 v162, v1, v162
	v_sub_f32_e32 v178, v178, v201
	v_mul_f32_e32 v185, 0x3fb8aa3b, v185
	v_exp_f32_e32 v184, v184
	v_add_f32_e32 v162, v2, v162
	v_sub_f32_e32 v179, v179, v201
	v_mul_f32_e32 v178, 0x3fb8aa3b, v178
	v_exp_f32_e32 v185, v185
	v_add_f32_e32 v162, v3, v162
	v_sub_f32_e32 v180, v180, v201
	v_mul_f32_e32 v179, 0x3fb8aa3b, v179
	v_exp_f32_e32 v178, v178
	v_add_f32_e32 v162, v182, v162
	v_sub_f32_e32 v181, v181, v201
	v_mul_f32_e32 v180, 0x3fb8aa3b, v180
	v_exp_f32_e32 v179, v179
	v_add_f32_e32 v162, v183, v162
	v_sub_f32_e32 v174, v174, v201
	v_mul_f32_e32 v181, 0x3fb8aa3b, v181
	v_exp_f32_e32 v180, v180
	v_add_f32_e32 v162, v184, v162
	v_sub_f32_e32 v175, v175, v201
	v_mul_f32_e32 v174, 0x3fb8aa3b, v174
	v_exp_f32_e32 v181, v181
	v_add_f32_e32 v162, v185, v162
	v_sub_f32_e32 v176, v176, v201
	v_mul_f32_e32 v175, 0x3fb8aa3b, v175
	v_exp_f32_e32 v174, v174
	v_add_f32_e32 v162, v178, v162
	v_sub_f32_e32 v177, v177, v201
	v_mul_f32_e32 v176, 0x3fb8aa3b, v176
	v_exp_f32_e32 v175, v175
	v_add_f32_e32 v162, v179, v162
	v_sub_f32_e32 v170, v170, v201
	v_mul_f32_e32 v177, 0x3fb8aa3b, v177
	v_exp_f32_e32 v176, v176
	v_add_f32_e32 v162, v180, v162
	v_sub_f32_e32 v171, v171, v201
	v_mul_f32_e32 v170, 0x3fb8aa3b, v170
	v_exp_f32_e32 v177, v177
	v_add_f32_e32 v162, v181, v162
	v_sub_f32_e32 v172, v172, v201
	v_mul_f32_e32 v171, 0x3fb8aa3b, v171
	v_exp_f32_e32 v170, v170
	v_add_f32_e32 v162, v174, v162
	v_sub_f32_e32 v173, v173, v201
	v_mul_f32_e32 v172, 0x3fb8aa3b, v172
	v_exp_f32_e32 v171, v171
	v_add_f32_e32 v162, v175, v162
	v_sub_f32_e32 v166, v166, v201
	v_mul_f32_e32 v173, 0x3fb8aa3b, v173
	v_exp_f32_e32 v172, v172
	v_add_f32_e32 v162, v176, v162
	v_sub_f32_e32 v167, v167, v201
	v_mul_f32_e32 v166, 0x3fb8aa3b, v166
	v_exp_f32_e32 v173, v173
	v_add_f32_e32 v162, v177, v162
	v_sub_f32_e32 v168, v168, v201
	v_mul_f32_e32 v167, 0x3fb8aa3b, v167
	v_exp_f32_e32 v226, v166
	v_add_f32_e32 v162, v170, v162
	v_sub_f32_e32 v169, v169, v201
	v_mul_f32_e32 v168, 0x3fb8aa3b, v168
	v_exp_f32_e32 v227, v167
	v_add_f32_e32 v162, v171, v162
	v_mul_f32_e32 v169, 0x3fb8aa3b, v169
	v_exp_f32_e32 v228, v168
	v_add_f32_e32 v162, v172, v162
	v_sub_f32_e32 v163, v163, v201
	v_sub_f32_e32 v158, v158, v201
	v_exp_f32_e32 v229, v169
	v_add_f32_e32 v162, v173, v162
	v_sub_f32_e32 v164, v164, v201
	v_mul_f32_e32 v163, 0x3fb8aa3b, v163
	v_mul_f32_e32 v158, 0x3fb8aa3b, v158
	v_add_f32_e32 v162, v226, v162
	v_sub_f32_e32 v165, v165, v201
	v_mul_f32_e32 v164, 0x3fb8aa3b, v164
	v_exp_f32_e32 v231, v163
	v_add_f32_e32 v162, v227, v162
	v_exp_f32_e32 v234, v158
	v_sub_f32_e32 v158, v159, v201
	v_mul_f32_e32 v165, 0x3fb8aa3b, v165
	v_exp_f32_e32 v232, v164
	v_add_f32_e32 v162, v228, v162
	v_mul_f32_e32 v158, 0x3fb8aa3b, v158
	v_exp_f32_e32 v233, v165
	v_add_f32_e32 v162, v229, v162
	v_exp_f32_e32 v235, v158
	v_sub_f32_e32 v158, v160, v201
	v_sub_f32_e32 v159, v188, v201
	v_add_f32_e32 v162, v230, v162
	v_mul_f32_e32 v158, 0x3fb8aa3b, v158
	v_mul_f32_e32 v159, 0x3fb8aa3b, v159
	v_add_f32_e32 v162, v231, v162
	v_exp_f32_e32 v236, v158
	v_sub_f32_e32 v158, v161, v201
	v_exp_f32_e32 v188, v159
	v_sub_f32_e32 v159, v189, v201
	v_add_f32_e32 v162, v232, v162
	v_mul_f32_e32 v158, 0x3fb8aa3b, v158
	v_mul_f32_e32 v159, 0x3fb8aa3b, v159
	v_add_f32_e32 v162, v233, v162
	v_exp_f32_e32 v237, v158
	v_exp_f32_e32 v189, v159
	v_sub_f32_e32 v159, v190, v201
	v_add_f32_e32 v158, v234, v162
	v_mul_f32_e32 v159, 0x3fb8aa3b, v159
	v_add_f32_e32 v158, v235, v158
	v_exp_f32_e32 v190, v159
	v_sub_f32_e32 v159, v191, v201
	v_add_f32_e32 v158, v236, v158
	v_mul_f32_e32 v159, 0x3fb8aa3b, v159
	v_add_f32_e32 v158, v237, v158
	v_exp_f32_e32 v191, v159
	v_add_f32_e32 v158, v188, v158
	v_add_f32_e32 v158, v189, v158
	v_add_f32_e32 v158, v190, v158
	v_add_f32_e32 v158, v191, v158
	ds_bpermute_b32 v159, v207, v158
	v_sub_f32_e32 v5, v239, v201
	v_mul_f32_e32 v5, 0x3fb8aa3b, v5
	v_exp_f32_e32 v5, v5
	v_cvt_pk_bf16_f32 v160, v182, v183
	s_waitcnt lgkmcnt(0)
; #define LAS __attribute__((address_space(3)))
; __device__ __forceinline__ unsigned pk2(float lo, float hi) { return f2bf(lo) | (f2bf(hi) << 16); }
; #define MFMA16(a, b, c) __builtin_amdgcn_mfma_f32_16x16x32_bf16((a), (b), (c), 0, 0, 0)
; __device__ __forceinline__ void attn_item(Frame& F, int item) {
;     ...
;         bf16x8 pf[5];
; #pragma unroll
;         for (int kk = 0; kk < 4; ++kk) pf[kk] = pack8(sc[2 * kk], sc[2 * kk + 1]);
;         pf[4] = pack8(sc[8], (f32x4){0.f, 0.f, 0.f, 0.f});
; #pragma unroll
;         for (int dt = 0; dt < 4; ++dt) {
;             f32x4 o = (f32x4){0.f, 0.f, 0.f, 0.f};
;             const LAS bf16* vrow = Vt + (16 * dt + l15) * VT2_STRIDE + 16 * w + 4 * quad;
; #pragma unroll
;             for (int kk = 0; kk < 5; ++kk) {
;                 const v2u lo = *(const LAS v2u*)(vrow + 32 * kk);
;                 v2u hi = (v2u){0u, 0u}; if (kk < 4) hi = *(const LAS v2u*)(vrow + 32 * kk + 16);
;                 o = MFMA16(join8(lo, hi), pf[kk], o);
;             }
;             v2u ow; ow.x = pk2(o[0] * il, o[1] * il); ow.y = pk2(o[2] * il, o[3] * il);
;             *(v2u*)(F.MIXED + row * D + 512 + qh * 64 + 16 * dt + 4 * quad) = ow;
;         }
	v_add_f32_e32 v158, v158, v159
	ds_bpermute_b32 v159, v208, v158
	v_cvt_pk_bf16_f32 v161, v184, v185
	v_cvt_pk_bf16_f32 v162, v178, v179
	v_cvt_pk_bf16_f32 v163, v180, v181
	v_cvt_pk_bf16_f32 v164, v174, v175
	s_waitcnt lgkmcnt(0)
	v_add_f32_e32 v158, v158, v159
	v_add_f32_e32 v5, v5, v158
	v_cvt_pk_bf16_f32 v158, v186, v1
	v_cvt_pk_bf16_f32 v159, v2, v3
	v_cvt_pk_bf16_f32 v165, v176, v177
	v_cvt_pk_bf16_f32 v170, v170, v171
	v_mfma_f32_16x16x32_bf16 v[166:169], v[78:81], v[158:161], 0
	v_cvt_pk_bf16_f32 v171, v172, v173
	v_cvt_pk_bf16_f32 v172, v226, v227
	v_cvt_pk_bf16_f32 v173, v228, v229
	v_mfma_f32_16x16x32_bf16 v[166:169], v[82:85], v[162:165], v[166:169]
	v_cvt_pk_bf16_f32 v174, v230, v231
	v_cvt_pk_bf16_f32 v175, v232, v233
	v_cvt_pk_bf16_f32 v176, v234, v235
	v_mfma_f32_16x16x32_bf16 v[166:169], v[86:89], v[170:173], v[166:169]
	v_cvt_pk_bf16_f32 v177, v236, v237
	v_rcp_f32_e32 v178, v5
	v_cvt_pk_bf16_f32 v2, v188, v189
	v_mfma_f32_16x16x32_bf16 v[166:169], v[90:93], v[174:177], v[166:169]
	v_cvt_pk_bf16_f32 v3, v190, v191
	v_mov_b32_e32 v5, v4
	s_nop 1
	v_mfma_f32_16x16x32_bf16 v[166:169], v[94:97], v[2:5], v[166:169]
	s_nop 7
	v_mov_b32_e32 v181, v168
	v_mov_b32_e32 v168, v167
	v_mov_b32_e32 v180, v166
	v_pk_mul_f32 v[182:183], v[168:169], v[178:179] op_sel_hi:[1,0]
	v_mfma_f32_16x16x32_bf16 v[166:169], v[98:101], v[158:161], 0
	v_mul_f32_e64 v180, v180, v178
	v_mul_f32_e64 v181, v181, v178
	v_and_b32_sdwa v1, v181, v225 dst_sel:DWORD dst_unused:UNUSED_PAD src0_sel:WORD_1 src1_sel:DWORD
	v_mfma_f32_16x16x32_bf16 v[166:169], v[102:105], v[162:165], v[166:169]
	v_and_b32_sdwa v179, v180, v225 dst_sel:DWORD dst_unused:UNUSED_PAD src0_sel:WORD_1 src1_sel:DWORD
	v_add3_u32 v179, v180, v179, s66
	v_add3_u32 v1, v181, v1, s66
	v_mfma_f32_16x16x32_bf16 v[166:169], v[106:109], v[170:173], v[166:169]
	v_and_b32_sdwa v180, v183, v225 dst_sel:DWORD dst_unused:UNUSED_PAD src0_sel:WORD_1 src1_sel:DWORD
	v_and_b32_sdwa v181, v182, v225 dst_sel:DWORD dst_unused:UNUSED_PAD src0_sel:WORD_1 src1_sel:DWORD
	v_add3_u32 v180, v183, v180, s66
	v_mfma_f32_16x16x32_bf16 v[166:169], v[110:113], v[174:177], v[166:169]
	v_add3_u32 v181, v182, v181, s66
	v_and_b32_e32 v180, 0xffff0000, v180
	v_and_b32_e32 v182, 0xffff0000, v181
	v_mfma_f32_16x16x32_bf16 v[166:169], v[114:117], v[2:5], v[166:169]
	v_or_b32_sdwa v181, v180, v1 dst_sel:DWORD dst_unused:UNUSED_PAD src0_sel:DWORD src1_sel:WORD_1
	v_or_b32_sdwa v180, v182, v179 dst_sel:DWORD dst_unused:UNUSED_PAD src0_sel:DWORD src1_sel:WORD_1
	v_lshl_add_u64 v[182:183], v[204:205], 0, s[82:83]
	global_store_dwordx2 v[182:183], v[180:181], off offset:-64
	s_add_u32 s82, s82, 0x80
	s_nop 2
	v_mov_b32_e32 v181, v168
	v_mov_b32_e32 v168, v167
	v_mov_b32_e32 v180, v166
	v_pk_mul_f32 v[184:185], v[168:169], v[178:179] op_sel_hi:[1,0]
	v_mfma_f32_16x16x32_bf16 v[166:169], v[118:121], v[158:161], 0
	v_mul_f32_e64 v180, v180, v178
	v_mul_f32_e64 v181, v181, v178
	s_addc_u32 s83, s83, 0
	v_and_b32_sdwa v1, v181, v225 dst_sel:DWORD dst_unused:UNUSED_PAD src0_sel:WORD_1 src1_sel:DWORD
	v_mfma_f32_16x16x32_bf16 v[158:161], v[138:141], v[158:161], 0
	v_and_b32_sdwa v179, v180, v225 dst_sel:DWORD dst_unused:UNUSED_PAD src0_sel:WORD_1 src1_sel:DWORD
	v_add3_u32 v179, v180, v179, s66
	v_add3_u32 v1, v181, v1, s66
	v_mfma_f32_16x16x32_bf16 v[166:169], v[122:125], v[162:165], v[166:169]
	v_and_b32_sdwa v180, v185, v225 dst_sel:DWORD dst_unused:UNUSED_PAD src0_sel:WORD_1 src1_sel:DWORD
	v_and_b32_sdwa v181, v184, v225 dst_sel:DWORD dst_unused:UNUSED_PAD src0_sel:WORD_1 src1_sel:DWORD
	v_add3_u32 v180, v185, v180, s66
	v_mfma_f32_16x16x32_bf16 v[158:161], v[142:145], v[162:165], v[158:161]
	v_add3_u32 v181, v184, v181, s66
	v_and_b32_e32 v180, 0xffff0000, v180
	v_and_b32_e32 v184, 0xffff0000, v181
	v_mfma_f32_16x16x32_bf16 v[166:169], v[126:129], v[170:173], v[166:169]
	v_or_b32_sdwa v181, v180, v1 dst_sel:DWORD dst_unused:UNUSED_PAD src0_sel:DWORD src1_sel:WORD_1
	v_or_b32_sdwa v180, v184, v179 dst_sel:DWORD dst_unused:UNUSED_PAD src0_sel:DWORD src1_sel:WORD_1
	global_store_dwordx2 v[182:183], v[180:181], off offset:-32
	v_mfma_f32_16x16x32_bf16 v[158:161], v[146:149], v[170:173], v[158:161]
	s_add_u32 s78, s78, 4
	s_addc_u32 s79, s79, 0
	s_cmpk_lg_i32 s82, 0x200
	v_mfma_f32_16x16x32_bf16 v[166:169], v[130:133], v[174:177], v[166:169]
	v_mfma_f32_16x16x32_bf16 v[158:161], v[150:153], v[174:177], v[158:161]
	v_mfma_f32_16x16x32_bf16 v[166:169], v[134:137], v[2:5], v[166:169]
	v_mfma_f32_16x16x32_bf16 v[158:161], v[154:157], v[2:5], v[158:161]
	s_nop 6
	v_mov_b32_e32 v181, v168
	v_mov_b32_e32 v168, v167
	v_mov_b32_e32 v180, v166
	v_pk_mul_f32 v[166:167], v[168:169], v[178:179] op_sel_hi:[1,0]
	v_pk_mul_f32 v[180:181], v[180:181], v[178:179] op_sel_hi:[1,0]
	v_and_b32_sdwa v163, v166, v225 dst_sel:DWORD dst_unused:UNUSED_PAD src0_sel:WORD_1 src1_sel:DWORD
	v_mov_b32_e32 v2, v158
	v_mov_b32_e32 v3, v160
	v_add3_u32 v163, v166, v163, s66
	v_pk_mul_f32 v[2:3], v[2:3], v[178:179] op_sel_hi:[1,0]
	v_mov_b32_e32 v160, v159
	v_and_b32_e32 v164, 0xffff0000, v163
	v_cvt_pk_bf16_f32 v163, v181, v167
	v_pk_mul_f32 v[158:159], v[160:161], v[178:179] op_sel_hi:[1,0]
	v_and_b32_sdwa v168, v180, v225 dst_sel:DWORD dst_unused:UNUSED_PAD src0_sel:WORD_1 src1_sel:DWORD
	v_add3_u32 v168, v180, v168, s66
	v_or_b32_sdwa v162, v164, v168 dst_sel:DWORD dst_unused:UNUSED_PAD src0_sel:DWORD src1_sel:WORD_1
	v_cvt_pk_bf16_f32 v3, v3, v159
	v_cvt_pk_bf16_f32 v2, v2, v158
	global_store_dwordx2 v[182:183], v[162:163], off
	global_store_dwordx2 v[182:183], v[2:3], off offset:32
	s_cbranch_scc0 .LBB0_485
; __device__ __forceinline__ unsigned pk2(float lo, float hi) { return f2bf(lo) | (f2bf(hi) << 16); }
; #define MFMA16(a, b, c) __builtin_amdgcn_mfma_f32_16x16x32_bf16((a), (b), (c), 0, 0, 0)
; __device__ __forceinline__ void attn_item(Frame& F, int item) {
;     ...
;         bf16x8 bq[2];
;         {
;             v4u qw[2]; float ss = 0.f;
; #pragma unroll
;             for (int ks = 0; ks < 2; ++ks) { qw[ks] = *(const v4u*)(F.PROJ + row * PW + C_AQ + qh * 64 + 32 * ks + 8 * quad);
; #pragma unroll
;                 for (int j = 0; j < 4; ++j) { const float a = bflo(qw[ks][j]), c = bfhi(qw[ks][j]); ss += a * a + c * c; } }
;             ss += __shfl_xor(ss, 16); ss += __shfl_xor(ss, 32);
;             const float rs = 0.125f * __builtin_amdgcn_rsqf(ss * (1.0f / 64.0f) + EPS);
; #pragma unroll
;             for (int ks = 0; ks < 2; ++ks) {
;                 const f32x4 g0 = *(const f32x4*)(F.qg + 32 * ks + 8 * quad), g1 = *(const f32x4*)(F.qg + 32 * ks + 8 * quad + 4);
;                 v4u o;
;                 o.x = pk2(bflo(qw[ks][0]) * rs * g0[0], bfhi(qw[ks][0]) * rs * g0[1]); o.y = pk2(bflo(qw[ks][1]) * rs * g0[2], bfhi(qw[ks][1]) * rs * g0[3]);
;                 o.z = pk2(bflo(qw[ks][2]) * rs * g1[0], bfhi(qw[ks][2]) * rs * g1[1]); o.w = pk2(bflo(qw[ks][3]) * rs * g1[2], bfhi(qw[ks][3]) * rs * g1[3]);
;                 bq[ks] = __builtin_bit_cast(bf16x8, o);
;             }
;         }
;         f32x4 sc[9];
; #pragma unroll
;         for (int kt = 0; kt < 9; ++kt) { sc[kt] = (f32x4){0.f, 0.f, 0.f, 0.f};
; #pragma unroll
;             for (int ks = 0; ks < 2; ++ks) sc[kt] = MFMA16(kf[kt][ks], bq[ks], sc[kt]); }
; #pragma unroll
;         for (int r = 0; r < 4; ++r) { if (!(l15 < 4 * quad + r)) sc[0][r] = NEG; if (!(l15 >= 4 * quad + r)) sc[8][r] = NEG; }
.LBB0_490:
	global_load_dword v239, v4, s[78:79]
	v_lshl_add_u64 v[2:3], v[202:203], 0, s[82:83]
	v_add_co_u32_e32 v2, vcc, 0x4001000, v2
	s_nop 1
	v_addc_co_u32_e32 v3, vcc, 0, v3, vcc
	global_load_dwordx4 v[158:161], v[192:193], off offset:128
	global_load_dwordx4 v[162:165], v[2:3], off offset:64
	global_load_dwordx4 v[166:169], v[2:3], off
	global_load_dwordx4 v[170:173], v[192:193], off
	global_load_dwordx4 v[174:177], v[192:193], off offset:16
	global_load_dwordx4 v[178:181], v[192:193], off offset:144
	s_andn2_b64 vcc, exec, s[80:81]
	s_waitcnt vmcnt(5)
	v_mov_b32_e32 v2, v158
	s_waitcnt vmcnt(4)
	v_lshlrev_b32_e32 v183, 16, v163
	s_waitcnt vmcnt(3)
	v_lshlrev_b32_e32 v189, 16, v167
	v_lshlrev_b32_e32 v188, 16, v166
	v_and_b32_e32 v167, 0xffff0000, v167
	v_and_b32_e32 v166, 0xffff0000, v166
	v_lshlrev_b32_e32 v191, 16, v169
	v_lshlrev_b32_e32 v190, 16, v168
	v_and_b32_e32 v169, 0xffff0000, v169
	v_and_b32_e32 v168, 0xffff0000, v168
	v_pk_mul_f32 v[230:231], v[166:167], v[166:167]
	v_pk_mul_f32 v[232:233], v[168:169], v[168:169]
	v_pk_fma_f32 v[230:231], v[188:189], v[188:189], v[230:231]
	v_lshlrev_b32_e32 v182, 16, v162
	v_and_b32_e32 v163, 0xffff0000, v163
	v_and_b32_e32 v162, 0xffff0000, v162
	v_pk_fma_f32 v[232:233], v[190:191], v[190:191], v[232:233]
	v_add_f32_e32 v1, v230, v231
	v_pk_mul_f32 v[226:227], v[162:163], v[162:163]
	v_add_f32_e32 v1, v232, v1
	v_lshlrev_b32_e32 v185, 16, v165
	v_lshlrev_b32_e32 v184, 16, v164
	v_and_b32_e32 v165, 0xffff0000, v165
	v_and_b32_e32 v164, 0xffff0000, v164
	v_pk_fma_f32 v[226:227], v[182:183], v[182:183], v[226:227]
	v_add_f32_e32 v1, v233, v1
	v_pk_mul_f32 v[228:229], v[164:165], v[164:165]
	v_add_f32_e32 v1, v226, v1
	v_pk_fma_f32 v[228:229], v[184:185], v[184:185], v[228:229]
	v_add_f32_e32 v1, v227, v1
	v_add_f32_e32 v1, v228, v1
	v_add_f32_e32 v1, v229, v1
	ds_bpermute_b32 v5, v207, v1
	s_waitcnt vmcnt(2)
	v_mov_b32_e32 v158, v170
	s_waitcnt vmcnt(1)
	v_mov_b32_e32 v170, v174
	s_waitcnt vmcnt(0)
	v_mov_b32_e32 v174, v178
	v_mov_b32_e32 v3, v160
	s_waitcnt lgkmcnt(0)
	v_add_f32_e32 v1, v1, v5
	ds_bpermute_b32 v5, v208, v1
	v_mov_b32_e32 v160, v159
	v_mov_b32_e32 v159, v172
	v_mov_b32_e32 v172, v171
	v_mov_b32_e32 v171, v176
	s_waitcnt lgkmcnt(0)
	v_add_f32_e32 v1, v1, v5
	v_fmamk_f32 v1, v1, 0x3c800000, v213
	v_rsq_f32_e32 v1, v1
	v_mov_b32_e32 v176, v175
	v_mov_b32_e32 v175, v180
	v_mov_b32_e32 v180, v179
	v_mul_f32_e32 v178, 0x3e000000, v1
	v_pk_mul_f32 v[188:189], v[178:179], v[188:189] op_sel_hi:[0,1]
	v_pk_mul_f32 v[190:191], v[178:179], v[190:191] op_sel_hi:[0,1]
	v_pk_mul_f32 v[168:169], v[178:179], v[168:169] op_sel_hi:[0,1]
	v_pk_mul_f32 v[166:167], v[178:179], v[166:167] op_sel_hi:[0,1]
	v_pk_mul_f32 v[162:163], v[178:179], v[162:163] op_sel_hi:[0,1]
	v_pk_mul_f32 v[184:185], v[178:179], v[184:185] op_sel_hi:[0,1]
	v_pk_mul_f32 v[164:165], v[178:179], v[164:165] op_sel_hi:[0,1]
	v_pk_mul_f32 v[158:159], v[158:159], v[188:189]
	v_pk_mul_f32 v[170:171], v[170:171], v[190:191]
	v_pk_mul_f32 v[168:169], v[176:177], v[168:169]
	v_pk_mul_f32 v[166:167], v[172:173], v[166:167]
	v_pk_mul_f32 v[160:161], v[160:161], v[162:163]
	v_pk_mul_f32 v[162:163], v[174:175], v[184:185]
	v_pk_mul_f32 v[164:165], v[180:181], v[164:165]
	v_bfe_u32 v1, v169, 16, 1
	v_bfe_u32 v5, v168, 16, 1
	v_bfe_u32 v174, v158, 16, 1
	v_bfe_u32 v175, v159, 16, 1
	v_bfe_u32 v176, v170, 16, 1
	v_bfe_u32 v177, v171, 16, 1
	v_pk_mul_f32 v[182:183], v[178:179], v[182:183] op_sel_hi:[0,1]
	v_bfe_u32 v172, v167, 16, 1
	v_bfe_u32 v173, v166, 16, 1
	v_bfe_u32 v178, v165, 16, 1
	v_bfe_u32 v180, v161, 16, 1
	v_bfe_u32 v181, v160, 16, 1
	v_bfe_u32 v185, v163, 16, 1
	v_add3_u32 v5, v168, v5, s66
	v_add3_u32 v1, v169, v1, s66
	v_add3_u32 v168, v171, v177, s66
	v_add3_u32 v169, v170, v176, s66
	v_add3_u32 v159, v159, v175, s66
	v_add3_u32 v158, v158, v174, s66
	v_add3_u32 v166, v166, v173, s66
	v_add3_u32 v167, v167, v172, s66
	v_add3_u32 v170, v160, v181, s66
	v_add3_u32 v171, v161, v180, s66
	v_add3_u32 v160, v165, v178, s66
	v_add3_u32 v161, v163, v185, s66
	v_lshrrev_b32_e32 v158, 16, v158
	v_lshrrev_b32_e32 v159, 16, v159
	v_lshrrev_b32_e32 v163, 16, v169
	v_lshrrev_b32_e32 v165, 16, v168
	v_pk_mul_f32 v[2:3], v[2:3], v[182:183]
	v_and_or_b32 v191, v1, s63, v165
	v_and_or_b32 v190, v5, s63, v163
	v_and_or_b32 v189, v167, s63, v159
	v_and_or_b32 v188, v166, s63, v158
	v_lshrrev_b32_e32 v5, 16, v161
	v_bfe_u32 v182, v2, 16, 1
	v_bfe_u32 v183, v3, 16, 1
	v_bfe_u32 v184, v162, 16, 1
	v_and_or_b32 v229, v160, s63, v5
	v_mfma_f32_16x16x32_bf16 v[158:161], v[6:9], v[188:191], 0
	v_bfe_u32 v179, v164, 16, 1
	v_add3_u32 v162, v162, v184, s66
	v_add3_u32 v3, v3, v183, s66
	v_add3_u32 v1, v2, v182, s66
	v_add3_u32 v164, v164, v179, s66
	v_lshrrev_b32_e32 v1, 16, v1
	v_lshrrev_b32_e32 v2, 16, v3
	v_lshrrev_b32_e32 v3, 16, v162
	v_and_or_b32 v228, v164, s63, v3
	v_and_or_b32 v227, v171, s63, v2
	v_and_or_b32 v226, v170, s63, v1
	v_mov_b32_e32 v2, s67
	s_nop 0
	v_mfma_f32_16x16x32_bf16 v[230:233], v[10:13], v[226:229], v[158:161]
	v_mfma_f32_16x16x32_bf16 v[158:161], v[14:17], v[188:191], 0
	v_mfma_f32_16x16x32_bf16 v[182:185], v[18:21], v[226:229], v[158:161]
	s_nop 5
	v_cndmask_b32_e64 v186, v2, v230, s[4:5]
	v_cndmask_b32_e64 v1, v224, v231, s[6:7]
	v_cndmask_b32_e64 v2, v224, v232, s[8:9]
	v_mfma_f32_16x16x32_bf16 v[158:161], v[22:25], v[188:191], 0
	v_cndmask_b32_e64 v3, v224, v233, s[10:11]
	v_mfma_f32_16x16x32_bf16 v[178:181], v[26:29], v[226:229], v[158:161]
	v_mfma_f32_16x16x32_bf16 v[158:161], v[30:33], v[188:191], 0
	v_mfma_f32_16x16x32_bf16 v[174:177], v[34:37], v[226:229], v[158:161]
	v_mfma_f32_16x16x32_bf16 v[158:161], v[38:41], v[188:191], 0
	v_mfma_f32_16x16x32_bf16 v[170:173], v[42:45], v[226:229], v[158:161]
	v_mfma_f32_16x16x32_bf16 v[158:161], v[46:49], v[188:191], 0
	v_mfma_f32_16x16x32_bf16 v[166:169], v[50:53], v[226:229], v[158:161]
	v_mfma_f32_16x16x32_bf16 v[158:161], v[54:57], v[188:191], 0
	v_mfma_f32_16x16x32_bf16 v[162:165], v[58:61], v[226:229], v[158:161]
	v_mfma_f32_16x16x32_bf16 v[158:161], v[62:65], v[188:191], 0
	v_mfma_f32_16x16x32_bf16 v[188:191], v[70:73], v[188:191], 0
	v_mfma_f32_16x16x32_bf16 v[158:161], v[66:69], v[226:229], v[158:161]
	v_mfma_f32_16x16x32_bf16 v[188:191], v[74:77], v[226:229], v[188:191]
	s_cbranch_vccnz .LBB0_489
; __device__ __forceinline__ void attn_item(Frame& F, int item) {
;     ...
;         if (qb == 0) {
; #pragma unroll
;             for (int kt = 0; kt < 9; ++kt)
; #pragma unroll
;                 for (int r = 0; r < 4; ++r) if (16 * w + 16 * kt + 4 * quad + r < 128) sc[kt][r] = NEG;
;         }
	v_cndmask_b32_e64 v3, v3, v224, s[12:13]
	v_cndmask_b32_e64 v2, v2, v224, s[12:13]
	v_cndmask_b32_e64 v1, v1, v224, s[12:13]
	v_cndmask_b32_e64 v186, v186, v224, s[12:13]
	v_cndmask_b32_e64 v185, v185, v224, s[14:15]
	v_cndmask_b32_e64 v184, v184, v224, s[14:15]
	v_cndmask_b32_e64 v183, v183, v224, s[14:15]
	v_cndmask_b32_e64 v182, v182, v224, s[14:15]
	v_cndmask_b32_e64 v181, v181, v224, s[16:17]
	v_cndmask_b32_e64 v180, v180, v224, s[16:17]
	v_cndmask_b32_e64 v179, v179, v224, s[16:17]
	v_cndmask_b32_e64 v178, v178, v224, s[16:17]
	v_cndmask_b32_e64 v177, v177, v224, s[18:19]
	v_cndmask_b32_e64 v176, v176, v224, s[18:19]
	v_cndmask_b32_e64 v175, v175, v224, s[18:19]
	v_cndmask_b32_e64 v174, v174, v224, s[18:19]
	v_cndmask_b32_e64 v173, v173, v224, s[20:21]
	v_cndmask_b32_e64 v172, v172, v224, s[20:21]
	v_cndmask_b32_e64 v171, v171, v224, s[20:21]
	v_cndmask_b32_e64 v170, v170, v224, s[20:21]
	v_cndmask_b32_e64 v169, v169, v224, s[22:23]
	v_cndmask_b32_e64 v168, v168, v224, s[22:23]
	v_cndmask_b32_e64 v167, v167, v224, s[22:23]
	v_cndmask_b32_e64 v166, v166, v224, s[22:23]
	v_cndmask_b32_e64 v165, v165, v224, s[24:25]
	v_cndmask_b32_e64 v164, v164, v224, s[24:25]
	v_cndmask_b32_e64 v163, v163, v224, s[24:25]
	v_cndmask_b32_e64 v162, v162, v224, s[24:25]
	v_cndmask_b32_e64 v161, v161, v224, s[26:27]
	v_cndmask_b32_e64 v160, v160, v224, s[26:27]
	v_cndmask_b32_e64 v159, v159, v224, s[26:27]
	v_cndmask_b32_e64 v158, v158, v224, s[26:27]
	s_branch .LBB0_489

; template <bool COOP>
; __global__ void __launch_bounds__(NWAVES * 64, 2) fwd(Args args) {
	.amdhsa_kernel _Z3fwdILb1EEv4Args
		.amdhsa_group_segment_fixed_size 0
		.amdhsa_private_segment_fixed_size 0
		.amdhsa_kernarg_size 384
		.amdhsa_user_sgpr_count 2
		.amdhsa_user_sgpr_dispatch_ptr 0
		.amdhsa_user_sgpr_queue_ptr 0
		.amdhsa_user_sgpr_kernarg_segment_ptr 1
		.amdhsa_user_sgpr_dispatch_id 0
		.amdhsa_user_sgpr_kernarg_preload_length 0
		.amdhsa_user_sgpr_kernarg_preload_offset 0
		.amdhsa_user_sgpr_private_segment_size 0
		.amdhsa_uses_dynamic_stack 0
		.amdhsa_enable_private_segment 0
		.amdhsa_system_sgpr_workgroup_id_x 1
		.amdhsa_system_sgpr_workgroup_id_y 0
		.amdhsa_system_sgpr_workgroup_id_z 0
		.amdhsa_system_sgpr_workgroup_info 0
		.amdhsa_system_vgpr_workitem_id 0
		.amdhsa_next_free_vgpr 240
		.amdhsa_next_free_sgpr 102
		.amdhsa_accum_offset 240
		.amdhsa_reserve_vcc 1
		.amdhsa_float_round_mode_32 0
		.amdhsa_float_round_mode_16_64 0
		.amdhsa_float_denorm_mode_32 3
		.amdhsa_float_denorm_mode_16_64 3
		.amdhsa_dx10_clamp 1
		.amdhsa_ieee_mode 1
		.amdhsa_fp16_overflow 0
		.amdhsa_tg_split 0
		.amdhsa_exception_fp_ieee_invalid_op 0
		.amdhsa_exception_fp_denorm_src 0
		.amdhsa_exception_fp_ieee_div_zero 0
		.amdhsa_exception_fp_ieee_overflow 0
		.amdhsa_exception_fp_ieee_underflow 0
		.amdhsa_exception_fp_ieee_inexact 0
		.amdhsa_exception_int_div_zero 0
	.end_amdhsa_kernel

; template <bool COOP>
; __global__ void __launch_bounds__(NWAVES * 64, 2) fwd(Args args) {
amdhsa.kernels:
  - .agpr_count:     0
    .args:
      - .offset:         0
        .size:           128
        .value_kind:     by_value
      - .offset:         128
        .size:           4
        .value_kind:     hidden_block_count_x
      - .offset:         132
        .size:           4
        .value_kind:     hidden_block_count_y
      - .offset:         136
        .size:           4
        .value_kind:     hidden_block_count_z
      - .offset:         140
        .size:           2
        .value_kind:     hidden_group_size_x
      - .offset:         142
        .size:           2
        .value_kind:     hidden_group_size_y
      - .offset:         144
        .size:           2
        .value_kind:     hidden_group_size_z
      - .offset:         146
        .size:           2
        .value_kind:     hidden_remainder_x
      - .offset:         148
        .size:           2
        .value_kind:     hidden_remainder_y
      - .offset:         150
        .size:           2
        .value_kind:     hidden_remainder_z
      - .offset:         168
        .size:           8
        .value_kind:     hidden_global_offset_x
      - .offset:         176
        .size:           8
        .value_kind:     hidden_global_offset_y
      - .offset:         184
        .size:           8
        .value_kind:     hidden_global_offset_z
      - .offset:         192
        .size:           2
        .value_kind:     hidden_grid_dims
      - .offset:         248
        .size:           4
        .value_kind:     hidden_dynamic_lds_size
    .group_segment_fixed_size: 0
    .kernarg_segment_align: 8
    .kernarg_segment_size: 384
    .language:       OpenCL C
    .language_version:
      - 2
      - 0
    .max_flat_workgroup_size: 512
    .name:           _Z3fwdILb1EEv4Args
    .private_segment_fixed_size: 0
    .sgpr_count:     108
    .sgpr_spill_count: 16
    .symbol:         _Z3fwdILb1EEv4Args.kd
    .uniform_work_group_size: 1
    .uses_dynamic_stack: false
    .vgpr_count:     240
    .vgpr_spill_count: 0
    .wavefront_size: 64
  - .agpr_count:     0
    .args:
      - .offset:         0
        .size:           128
        .value_kind:     by_value
      - .offset:         128
        .size:           4
        .value_kind:     hidden_block_count_x
      - .offset:         132
        .size:           4
        .value_kind:     hidden_block_count_y
      - .offset:         136
        .size:           4
        .value_kind:     hidden_block_count_z
      - .offset:         140
        .size:           2
        .value_kind:     hidden_group_size_x
      - .offset:         142
        .size:           2
        .value_kind:     hidden_group_size_y
      - .offset:         144
        .size:           2
        .value_kind:     hidden_group_size_z
      - .offset:         146
        .size:           2
        .value_kind:     hidden_remainder_x
      - .offset:         148
        .size:           2
        .value_kind:     hidden_remainder_y
      - .offset:         150
        .size:           2
        .value_kind:     hidden_remainder_z
      - .offset:         168
        .size:           8
        .value_kind:     hidden_global_offset_x
      - .offset:         176
        .size:           8
        .value_kind:     hidden_global_offset_y
      - .offset:         184
        .size:           8
        .value_kind:     hidden_global_offset_z
      - .offset:         192
        .size:           2
        .value_kind:     hidden_grid_dims
      - .offset:         248
        .size:           4
        .value_kind:     hidden_dynamic_lds_size
    .group_segment_fixed_size: 0
    .kernarg_segment_align: 8
    .kernarg_segment_size: 384
    .language:       OpenCL C
    .language_version:
      - 2
      - 0
    .max_flat_workgroup_size: 512
    .name:           _Z3fwdILb0EEv4Args
    .private_segment_fixed_size: 0
    .sgpr_count:     104
    .sgpr_spill_count: 0
    .symbol:         _Z3fwdILb0EEv4Args.kd
    .uniform_work_group_size: 1
    .uses_dynamic_stack: false
    .vgpr_count:     238
    .vgpr_spill_count: 0
    .wavefront_size: 64
